# baseline (speedup 1.0000x reference)
; #define LAS __attribute__((address_space(3)))
; #define GAS __attribute__((address_space(1)))
; #define PARAMS_LOCAL KParams PP_ = kparams(); const __attribute__((address_space(4))) Params& P = *PP_;
; __device__ __forceinline__ unsigned pk2(float lo, float hi) { unsigned r; asm("s_nop 1\n\tv_cvt_pk_bf16_f32 %0, %1, %2" : "=v"(r) : "v"(lo), "v"(hi)); return r; }
; __device__ __forceinline__ void tr_wave_job(const GAS float* src0, const GAS float* src1, int ld, int mode, GAS bf16* dst, int K, int ldd, int n0, int k0, int lane, int wid, const GAS float* gk) {
;   const int n = n0 + lane;
;   const GAS float* s = src0; int col = n;
;   if (mode == 1) { const int blk = n >> 4; col = (blk >> 1) * 16 + (n & 15); s = (blk & 1) ? src1 : src0; }
;   else if (mode == 2) {
;     if (n < 1024) { const int c = n & 255, tb = n & ~255; col = tb + ((c >> 5) & 3) * 64 + (c >> 7) * 32 + (c & 31); }
;     else if (n < 1536) col = n; else col = n + 8;
;   }
;   const GAS float* sp = s + (size_t)k0 * ld + col;
;   LAS unsigned char* scr = (LAS unsigned char*)smem_raw + wid * 8192;
;   float v[64];
; #pragma unroll
;   for (int kk = 0; kk < 64; ++kk) v[kk] = sp[(size_t)kk * ld];
;   if (gk) {
; #pragma unroll
;     for (int kk = 0; kk < 64; ++kk) v[kk] *= gk[k0 + kk];
;   }
; #pragma unroll
;   for (int q = 0; q < 8; ++q) {
;     u32x4 o = {pk2(v[8 * q + 0], v[8 * q + 1]), pk2(v[8 * q + 2], v[8 * q + 3]), pk2(v[8 * q + 4], v[8 * q + 5]), pk2(v[8 * q + 6], v[8 * q + 7])};
;     *(LAS u32x4*)(scr + (lane * 8 + (q ^ (lane & 7))) * 16) = o;
; __device__ __forceinline__ void convert_jobs(int j0, int j1, int wrank, int nwaves, int lane, int wid) {
;   PARAMS_LOCAL
;   GAS unsigned char* ws = (GAS unsigned char*)P.ws; asm volatile("" : "+s"(ws));
;   for (int job = j0 + wrank; job < j1; job += nwaves) {
;     int r = job; const GAS float* s0; const GAS float* s1 = nullptr; const GAS float* gk = nullptr; int ld, mode = 0, K; GAS bf16* dst;
;     if (r < J_GU) { s0 = (const GAS float*)P.ffn1_wg; s1 = (const GAS float*)P.ffn1_wu; ld = FF; mode = 1; K = DM; dst = (GAS bf16*)(ws + OFF_WGU1); gk = (const GAS float*)P.ffn1_norm; }
.LBB0_22:
	s_or_b64 exec, exec, s[4:5]
	s_mov_b64 s[10:11], s[0:1]
	s_waitcnt lgkmcnt(0)
	s_load_dwordx2 s[8:9], s[10:11], 0xb0
	s_barrier
	v_mov_b32_e32 v3, v170
	s_waitcnt lgkmcnt(0)
	global_load_dword v171, v[172:173], off
	v_ashrrev_i32_e32 v8, 6, v3
	s_mov_b64 s[16:17], s[0:1]
	s_movk_i32 s3, 0x580
	v_lshl_add_u32 v50, s2, 3, v8
	s_load_dwordx2 s[14:15], s[16:17], 0xb0
	v_and_b32_e32 v51, 63, v3
	v_cmp_gt_i32_e32 vcc, s3, v50
	s_waitcnt lgkmcnt(0)
	s_waitcnt vmcnt(0)
	v_lshlrev_b32_e32 v78, 3, v171
	s_and_saveexec_b64 s[12:13], vcc
	s_cbranch_execz .LBB0_27
	s_load_dwordx4 s[4:7], s[16:17], 0x10
	s_load_dwordx2 s[18:19], s[16:17], 0x20
	v_mov_b32_e32 v2, 0x100
	v_lshrrev_b32_e32 v80, 3, v51
	v_and_b32_e32 v1, 15, v3
	v_and_b32_e32 v4, 16, v3
	v_lshl_add_u32 v5, v8, 13, v2
	v_and_b32_e32 v2, 7, v3
	v_bitop3_b32 v3, v80, v3, 7 bitop3:0x78
	v_lshl_add_u32 v79, v51, 7, v5
	v_lshl_add_u32 v16, v3, 4, v5
	s_waitcnt lgkmcnt(0)
	v_mov_b32_e32 v3, s19
	v_mov_b32_e32 v5, s7
	v_cmp_eq_u32_e32 vcc, 0, v4
	v_mov_b32_e32 v4, s6
	v_lshlrev_b32_e32 v2, 4, v2
	v_cndmask_b32_e32 v5, v3, v5, vcc
	v_mov_b32_e32 v3, s18
	v_or_b32_e32 v81, 8, v80
	v_or_b32_e32 v82, 16, v80
	v_or_b32_e32 v83, 24, v80
	v_or_b32_e32 v84, 32, v80
	v_or_b32_e32 v85, 40, v80
	v_or_b32_e32 v86, 48, v80
	v_or_b32_e32 v87, 56, v80
	v_cndmask_b32_e32 v4, v3, v4, vcc
	v_mov_b32_e32 v3, 0
	v_xor_b32_e32 v9, 16, v2
	v_xor_b32_e32 v10, 32, v2
	v_xor_b32_e32 v11, 48, v2
	v_xor_b32_e32 v12, 64, v2
	v_xor_b32_e32 v13, 0x50, v2
	v_xor_b32_e32 v14, 0x60, v2
	v_xor_b32_e32 v15, 0x70, v2
	v_lshlrev_b32_e32 v17, 7, v80
	v_lshlrev_b32_e32 v18, 7, v81
	v_lshlrev_b32_e32 v19, 7, v82
	v_lshlrev_b32_e32 v20, 7, v83
	v_lshlrev_b32_e32 v21, 7, v84
	v_lshlrev_b32_e32 v22, 7, v85
	v_lshlrev_b32_e32 v23, 7, v86
	v_lshlrev_b32_e32 v24, 7, v87
	s_cmp_lg_u64 s[4:5], 0
	v_lshl_add_u64 v[6:7], s[14:15], 0, v[2:3]
	v_lshlrev_b32_e32 v3, 6, v8
	s_mov_b64 s[6:7], 0
	v_lshl_add_u32 v3, s2, 9, v3
	v_lshlrev_b32_e32 v88, 6, v78
	s_movk_i32 s3, 0x2c00
	s_movk_i32 s16, 0x2000
	s_movk_i32 s17, 0x5000
	s_mov_b32 s18, 0x8000
	s_mov_b32 s19, 0xb000
	s_mov_b32 s20, 0xd000
	s_mov_b32 s21, 0x10000
	s_mov_b32 s22, 0x13000
	s_mov_b32 s23, 0x16000
	s_mov_b32 s24, 0x18000
	s_mov_b32 s25, 0x1b000
	s_mov_b32 s26, 0x1e000
	s_mov_b32 s27, 0x21000
	s_mov_b32 s28, 0x23000
	s_mov_b32 s29, 0x26000
	s_mov_b32 s30, 0x29000
	s_mov_b32 s31, 0x2c000
	s_mov_b32 s33, 0x2e000
	s_mov_b32 s34, 0x31000
	s_mov_b32 s35, 0x34000
	s_mov_b32 s36, 0x37000
	s_mov_b32 s37, 0x39000
	s_mov_b32 s38, 0x3c000
	s_mov_b32 s39, 0x3f000
	s_mov_b32 s40, 0x42000
	s_mov_b32 s41, 0x44000
	s_mov_b32 s42, 0x47000
	s_mov_b32 s43, 0x4a000
	s_mov_b32 s44, 0x4d000
	s_mov_b32 s45, 0x4f000
	s_mov_b32 s46, 0x52000
	s_mov_b32 s47, 0x55000
	s_mov_b32 s48, 0x58000
	s_mov_b32 s49, 0x5a000
	s_mov_b32 s50, 0x5d000
	s_mov_b32 s51, 0x60000
	s_mov_b32 s52, 0x63000
	s_mov_b32 s53, 0x65000
	s_mov_b32 s54, 0x68000
	s_mov_b32 s55, 0x6b000
	s_mov_b32 s56, 0x6e000
	s_mov_b32 s57, 0x70000
	s_mov_b32 s58, 0x73000
	s_mov_b32 s59, 0x76000
	s_mov_b32 s60, 0x79000
	s_mov_b32 s61, 0x7b000
	s_mov_b32 s62, 0x7e000
	s_mov_b32 s63, 0x81000
	s_mov_b32 s64, 0x84000
	s_mov_b32 s65, 0x86000
	s_mov_b32 s66, 0x89000
	s_mov_b32 s67, 0x8c000
	s_mov_b32 s68, 0x8f000
	s_mov_b32 s69, 0x91000
	s_mov_b32 s70, 0x94000
	s_mov_b32 s71, 0x97000
	s_mov_b32 s72, 0x9a000
	s_mov_b32 s73, 0x9c000
	s_mov_b32 s74, 0x9f000
	s_mov_b32 s75, 0xa2000
	s_mov_b32 s76, 0xa5000
	s_cselect_b64 s[14:15], -1, 0
	v_add_u32_e32 v89, v79, v9
	v_add_u32_e32 v90, v79, v10
	v_add_u32_e32 v91, v79, v11
	v_add_u32_e32 v92, v79, v12
	v_add_u32_e32 v93, v79, v13
	v_add_u32_e32 v94, v79, v14
	v_add_u32_e32 v95, v79, v15
	v_add_u32_e32 v96, v16, v17
	v_add_u32_e32 v97, v16, v18
	v_add_u32_e32 v98, v16, v19
	v_add_u32_e32 v99, v16, v20
	v_add_u32_e32 v100, v16, v21
	v_add_u32_e32 v101, v16, v22
	v_add_u32_e32 v102, v16, v23
	v_add_u32_e32 v103, v16, v24
	s_movk_i32 s77, 0x57f
	v_mov_b32_e32 v104, v50
	s_branch .LBB0_25

; #define GAS __attribute__((address_space(1)))
; #define PARAMS_LOCAL KParams PP_ = kparams(); const __attribute__((address_space(4))) Params& P = *PP_;
; __device__ __forceinline__ int ugrid() { return __builtin_amdgcn_readfirstlane((int)gridDim.x); }
; __device__ __forceinline__ int ubid() { return __builtin_amdgcn_readfirstlane((int)blockIdx.x); }
; __device__ __forceinline__ int tile_first() {
;   const int G = ugrid(), b = ubid();
;   return ((G & 7) == 0) ? (b & 7) * (G >> 3) + (b >> 3) : b;
; __device__ __forceinline__ void phase_up(int pass) {
;   PARAMS_LOCAL
;   GAS unsigned char* ws = (GAS unsigned char*)P.ws; asm volatile("" : "+s"(ws));
;   const GAS bf16* Wgu = (const GAS bf16*)(ws + (pass ? OFF_WGU2 : OFF_WGU1));
;   const GAS bf16* A = (const GAS bf16*)(ws + OFF_XG);
;   GAS bf16* act = (GAS bf16*)(ws + OFF_RA);
;   const GAS float* ssq = (const GAS float*)(ws + OFF_SSQ);
;   constexpr int nN = 22, NT_ = 64 * nN;
;   int L = tile_first(), par = 0, pm, pn;
;   if (L < NT_) { tile_coords(L, nN, pm, pn); gemm_prefetch<DM>(A, Wgu, pm * 256, pn * 256); load_rr(ssq, pm * 256, 0); }
;   while (L < NT_) {
.LBB0_78:
	s_or_b64 exec, exec, s[4:5]
	s_mov_b64 s[4:5], s[0:1]
	v_readfirstlane_b32 s6, v171
	s_load_dwordx2 s[4:5], s[4:5], 0xb0
	s_barrier
	s_and_b32 s3, s6, 7
	s_cmp_lg_u32 s3, 0
	s_mov_b32 s3, s2
	s_waitcnt lgkmcnt(0)
	s_cbranch_scc0 .LBB0_80
	s_cmpk_gt_i32 s3, 0x57f
	s_cbranch_scc0 .LBB0_81
	s_branch .LBB0_95

; __device__ __forceinline__ int ugrid() { return __builtin_amdgcn_readfirstlane((int)gridDim.x); }
; __device__ __forceinline__ int ubid() { return __builtin_amdgcn_readfirstlane((int)blockIdx.x); }
; __device__ __forceinline__ int tile_first() {
;   const int G = ugrid(), b = ubid();
;   return ((G & 7) == 0) ? (b & 7) * (G >> 3) + (b >> 3) : b;
; template <int K, int LD>
; __device__ __forceinline__ void phase_resid(int mode) {
;     ...
;   constexpr int nN = 4, NT_ = 64 * nN;
;   int L = tile_first(), pm, pn;
;   if (L < NT_) { tile_coords(L, nN, pm, pn); gemm_prefetch<K, LD>(A, Wt, pm * 256, pn * 256); }
;   while (L < NT_) {
.LBB0_220:
	s_or_b64 exec, exec, s[4:5]
	v_readfirstlane_b32 s8, v171
	s_mov_b64 s[4:5], s[0:1]
	s_and_b32 s3, s8, 7
	s_load_dwordx2 s[6:7], s[4:5], 0xb0
	s_barrier
	s_cmp_lg_u32 s3, 0
	s_mov_b32 s3, s2
	s_waitcnt lgkmcnt(0)
	s_cbranch_scc1 .LBB0_222
	s_and_b32 s3, s2, 7
	s_ashr_i32 s8, s8, 3
	s_mul_i32 s3, s8, s3
	s_ashr_i32 s8, s2, 3
	s_add_i32 s3, s3, s8

; __device__ __forceinline__ int ugrid() { return __builtin_amdgcn_readfirstlane((int)gridDim.x); }
; __device__ __forceinline__ int ubid() { return __builtin_amdgcn_readfirstlane((int)blockIdx.x); }
; __device__ __forceinline__ int tile_first() {
;   const int G = ugrid(), b = ubid();
;   return ((G & 7) == 0) ? (b & 7) * (G >> 3) + (b >> 3) : b;
; __device__ __forceinline__ void phase_inproj() {
;     ...
;   constexpr int nN = 20, NT_ = 64 * nN;
;   int L = tile_first(), par = 0, pm_, pn_;
;   if (L < NT_) { tile_coords(L, nN, pm_, pn_); gemm_prefetch<DM>(A, Wt, pm_ * 256, pn_ * 256); load_rr(ssq, pm_ * 256, 0); }
;   while (L < NT_) {
.LBB0_336:
	s_or_b64 exec, exec, s[4:5]
	v_readfirstlane_b32 s4, v171
	s_mov_b64 s[6:7], s[0:1]
	s_and_b32 s3, s4, 7
	s_load_dwordx2 s[10:11], s[6:7], 0xb0
	s_barrier
	s_cmp_lg_u32 s3, 0
	s_mov_b32 s3, s2
	s_waitcnt lgkmcnt(0)
	s_cbranch_scc1 .LBB0_338
	s_and_b32 s3, s2, 7
	s_ashr_i32 s4, s4, 3
	s_mul_i32 s3, s4, s3
	s_ashr_i32 s4, s2, 3
	s_add_i32 s3, s3, s4

; #define GAS __attribute__((address_space(1)))
; #define PARAMS_LOCAL KParams PP_ = kparams(); const __attribute__((address_space(4))) Params& P = *PP_;
; __device__ __forceinline__ void phase_attn() {
;   PARAMS_LOCAL
;   GAS unsigned char* ws = (GAS unsigned char*)P.ws; asm volatile("" : "+s"(ws));
;   float gq = 0.f, gk = 0.f;
;   for (int i = 0; i < 64; ++i) { gq = fmaxf(gq, fabsf(((const GAS float*)P.q_norm)[i])); gk = fmaxf(gk, fabsf(((const GAS float*)P.k_norm)[i])); }
;   const float bq2 = 8.f * gq * gk * 1.02f * LOG2E;
.LBB0_417:
	s_or_b64 exec, exec, s[4:5]
	s_mov_b64 s[10:11], s[0:1]
	s_load_dwordx2 s[8:9], s[10:11], 0xb0
	s_barrier
	s_waitcnt lgkmcnt(0)
	s_load_dwordx4 s[4:7], s[10:11], 0x48
	s_mov_b64 s[10:11], 0
	v_mov_b32_e32 v3, 0
	v_mov_b32_e32 v2, 0
	v_mov_b32_e32 v4, 0

; __device__ __forceinline__ int ugrid() { return __builtin_amdgcn_readfirstlane((int)gridDim.x); }
; __device__ __forceinline__ int ubid() { return __builtin_amdgcn_readfirstlane((int)blockIdx.x); }
; __device__ __forceinline__ int tile_first() {
;   const int G = ugrid(), b = ubid();
;   return ((G & 7) == 0) ? (b & 7) * (G >> 3) + (b >> 3) : b;
; __device__ __forceinline__ void phase_branch() {
;     ...
;   constexpr int nN = 4, NT_ = 64 * nN;
;   int L = tile_first(), pm, pn;
;   if (L < NT_) { tile_coords(L, nN, pm, pn); gemm_prefetch<AW>(A1, W1, pm * 256, pn * 256); }
;   while (L < NT_) {
.LBB0_701:
	s_or_b64 exec, exec, s[4:5]
	s_mov_b64 s[4:5], s[0:1]
	s_load_dwordx2 s[8:9], s[4:5], 0xb0
	s_barrier
	v_readfirstlane_b32 s4, v171
	s_and_b32 s3, s4, 7
	s_cmp_lg_u32 s3, 0
	s_mov_b32 s3, s2
	s_waitcnt lgkmcnt(0)
	s_cbranch_scc0 .LBB0_703
	s_cmpk_gt_i32 s3, 0xff
	s_cbranch_scc0 .LBB0_704
	s_branch .LBB0_720

; __device__ __forceinline__ int ugrid() { return __builtin_amdgcn_readfirstlane((int)gridDim.x); }
; __device__ __forceinline__ int ubid() { return __builtin_amdgcn_readfirstlane((int)blockIdx.x); }
; __device__ __forceinline__ int tile_first() {
;   const int G = ugrid(), b = ubid();
;   return ((G & 7) == 0) ? (b & 7) * (G >> 3) + (b >> 3) : b;
; template <int K, int LD>
; __device__ __forceinline__ void phase_resid(int mode) {
;     ...
;   constexpr int nN = 4, NT_ = 64 * nN;
;   int L = tile_first(), pm, pn;
;   if (L < NT_) { tile_coords(L, nN, pm, pn); gemm_prefetch<K, LD>(A, Wt, pm * 256, pn * 256); }
;   while (L < NT_) {
.LBB0_757:
	s_or_b64 exec, exec, s[4:5]
	s_mov_b64 s[4:5], s[0:1]
	v_readfirstlane_b32 s6, v171
	s_load_dwordx2 s[4:5], s[4:5], 0xb0
	s_barrier
	s_and_b32 s3, s6, 7
	s_cmp_lg_u32 s3, 0
	s_mov_b32 s3, s2
	s_waitcnt lgkmcnt(0)
	s_cbranch_scc1 .LBB0_759
	s_and_b32 s3, s2, 7
	s_ashr_i32 s6, s6, 3
	s_mul_i32 s3, s6, s3
	s_ashr_i32 s6, s2, 3
	s_add_i32 s3, s3, s6

; #define GAS __attribute__((address_space(1)))
; #define PARAMS_LOCAL KParams PP_ = kparams(); const __attribute__((address_space(4))) Params& P = *PP_;
; __device__ __forceinline__ int ugrid() { return __builtin_amdgcn_readfirstlane((int)gridDim.x); }
; __device__ __forceinline__ int ubid() { return __builtin_amdgcn_readfirstlane((int)blockIdx.x); }
; __device__ __forceinline__ int tile_first() {
;   const int G = ugrid(), b = ubid();
;   return ((G & 7) == 0) ? (b & 7) * (G >> 3) + (b >> 3) : b;
; __device__ __forceinline__ void phase_up(int pass) {
;   PARAMS_LOCAL
;   GAS unsigned char* ws = (GAS unsigned char*)P.ws; asm volatile("" : "+s"(ws));
;   const GAS bf16* Wgu = (const GAS bf16*)(ws + (pass ? OFF_WGU2 : OFF_WGU1));
;   const GAS bf16* A = (const GAS bf16*)(ws + OFF_XG);
;   GAS bf16* act = (GAS bf16*)(ws + OFF_RA);
;   const GAS float* ssq = (const GAS float*)(ws + OFF_SSQ);
;   constexpr int nN = 22, NT_ = 64 * nN;
;   int L = tile_first(), par = 0, pm, pn;
;   if (L < NT_) { tile_coords(L, nN, pm, pn); gemm_prefetch<DM>(A, Wgu, pm * 256, pn * 256); load_rr(ssq, pm * 256, 0); }
;   while (L < NT_) {
.LBB0_873:
	s_or_b64 exec, exec, s[4:5]
	s_mov_b64 s[4:5], s[0:1]
	s_load_dwordx2 s[8:9], s[4:5], 0xb0
	s_barrier
	v_readfirstlane_b32 s4, v171
	s_and_b32 s3, s4, 7
	s_cmp_lg_u32 s3, 0
	s_mov_b32 s3, s2
	s_waitcnt lgkmcnt(0)
	s_cbranch_scc0 .LBB0_875
	s_cmpk_gt_i32 s3, 0x57f
	s_cbranch_scc0 .LBB0_876
	s_branch .LBB0_890

; __device__ __forceinline__ int ugrid() { return __builtin_amdgcn_readfirstlane((int)gridDim.x); }
; __device__ __forceinline__ int ubid() { return __builtin_amdgcn_readfirstlane((int)blockIdx.x); }
; __device__ __forceinline__ int tile_first() {
;   const int G = ugrid(), b = ubid();
;   return ((G & 7) == 0) ? (b & 7) * (G >> 3) + (b >> 3) : b;
; template <int K, int LD>
; __device__ __forceinline__ void phase_resid(int mode) {
;     ...
;   constexpr int nN = 4, NT_ = 64 * nN;
;   int L = tile_first(), pm, pn;
;   if (L < NT_) { tile_coords(L, nN, pm, pn); gemm_prefetch<K, LD>(A, Wt, pm * 256, pn * 256); }
;   while (L < NT_) {
.LBB0_1095:
	s_or_b64 exec, exec, s[4:5]
	s_mov_b64 s[4:5], s[0:1]
	s_load_dwordx2 s[6:7], s[4:5], 0xb0
	s_barrier
	v_readfirstlane_b32 s4, v171
	s_and_b32 s3, s4, 7
	s_cmp_lg_u32 s3, 0
	s_mov_b32 s3, s2
	s_waitcnt lgkmcnt(0)
	s_cbranch_scc1 .LBB0_1097
	s_and_b32 s3, s2, 7
	s_ashr_i32 s4, s4, 3
	s_mul_i32 s3, s4, s3
	s_ashr_i32 s4, s2, 3
	s_add_i32 s3, s3, s4

; __device__ __forceinline__ int ugrid() { return __builtin_amdgcn_readfirstlane((int)gridDim.x); }
; __device__ __forceinline__ int ubid() { return __builtin_amdgcn_readfirstlane((int)blockIdx.x); }
; __device__ __forceinline__ int tile_first() {
;   const int G = ugrid(), b = ubid();
;   return ((G & 7) == 0) ? (b & 7) * (G >> 3) + (b >> 3) : b;
; __device__ __forceinline__ void phase_ple() {
;     ...
;   constexpr int nN = 4, NT_ = 64 * nN;
;   int L = tile_first(), par = 0, pm, pn;
;   if (L < NT_) { tile_coords(L, nN, pm, pn); gemm_prefetch<PLE>(A1, W1, pm * 256, pn * 256); load_rr(ssq, pm * 256, 0); }
;   while (L < NT_) {
.LBB0_1211:
	s_or_b64 exec, exec, s[4:5]
	v_readfirstlane_b32 s3, v171
	s_mov_b64 s[4:5], s[0:1]
	s_and_b32 s6, s3, 7
	s_load_dwordx2 s[14:15], s[4:5], 0xb0
	s_barrier
	s_cmp_lg_u32 s6, 0
	s_waitcnt lgkmcnt(0)
	s_cbranch_scc0 .LBB0_1213
	s_cmpk_gt_i32 s2, 0xff
	s_cbranch_scc0 .LBB0_1214
	s_branch .LBB0_1232
